# scan loop: o rows leave as one 8-byte store per lane after a 4x4 in-quad transpose (was four 2-byte stores), the four o^2 row sums in one store, U and gc staged only by the waves holding distinct data
# speedup vs baseline: 1.0330x; 1.0069x over previous
; #define LAS __attribute__((address_space(3)))
; __device__ __forceinline__ void scan_unit(LAS unsigned char* lds, int uidx, const bf16* Qg, const bf16* Kg, bf16* Vg, const bf16* KT, const bf16* QK, const float* GC, float* SSQ, float* sp_gdn) {
;     const int tid = threadIdx.x, lane = tid & 63, s = __builtin_amdgcn_readfirstlane(tid >> 6);
;     const int xc = uidx & 7, yy = uidx >> 3, slab = yy & 3, bh = xc * 8 + (yy >> 2), b = bh >> 3, h = bh & 7;
;     LAS bf16* St = (LAS bf16*)lds; LAS bf16* Vt = St + 2 * 32 * 136; LAS bf16* Vts = Vt + 32 * 72;
;     const int ti = s >> 1, c = s & 1, li = lane & 15, lq = lane >> 4;
;     f32x4 S0 = (f32x4){0.f, 0.f, 0.f, 0.f}, S1 = S0;
;     const int ucol = h * 128 + slab * 32 + 16 * c + li;
;     ScanFrag cur, nxt;
;     scan_load(cur, 0, b, h, ti, s, li, lq, ucol, Qg, Kg, Vg, KT, QK, GC);
.LBB0_832:
	s_mov_b64 s[0:1], s[56:57]
	s_load_dwordx2 s[0:1], s[0:1], 0x108
	s_mov_b64 s[6:7], s[56:57]
	s_load_dwordx2 s[6:7], s[6:7], 0x108
	s_mov_b64 s[14:15], s[56:57]
	s_waitcnt lgkmcnt(0)
	s_add_u32 s18, s0, 0x4bb0000
	s_addc_u32 s19, s1, 0
	s_mov_b64 s[0:1], s[56:57]
	s_add_u32 s22, s6, 0x6c30000
	s_load_dwordx2 s[20:21], s[14:15], 0x108
	s_addc_u32 s23, s7, 0
	s_load_dwordx2 s[0:1], s[0:1], 0x108
	s_mov_b64 s[6:7], s[56:57]
	s_load_dwordx2 s[6:7], s[6:7], 0x108
	s_mov_b64 s[14:15], s[56:57]
	s_load_dwordx2 s[24:25], s[14:15], 0x108
	s_waitcnt lgkmcnt(0)
	s_add_u32 s28, s0, 0xad30000
	s_addc_u32 s29, s1, 0
	s_add_u32 s30, s6, 0xcdb0000
	s_addc_u32 s31, s7, 0
	s_add_u32 s39, s24, 0xef34000
	s_mov_b64 s[0:1], s[56:57]
	s_addc_u32 s42, s25, 0
	s_lshl_b32 s6, s36, 3
	s_ashr_i32 s7, s36, 5
	s_load_dwordx2 s[26:27], s[0:1], 0x108
	v_readfirstlane_b32 s0, v154
	s_bfe_u32 s1, s36, 0x20003
	s_and_b32 s6, s6, 56
	s_and_b32 s38, s7, 7
	s_add_i32 s6, s6, s7
	s_bfe_u32 s17, s0, 0x10006
	s_lshl_b32 s7, s38, 7
	s_lshl_b32 s37, s1, 5
	s_lshr_b32 s40, s0, 6
	s_ashr_i32 s34, s6, 3
	v_lshl_or_b32 v34, s17, 4, v156
	s_or_b32 s7, s7, s37
	s_lshr_b32 s0, s0, 3
	v_or_b32_e32 v4, s7, v34
	s_lshl_b32 s16, s34, 11
	s_and_b32 s7, s0, 0x1ffffff0
	s_add_i32 s0, s7, s16
	v_or_b32_e32 v76, s0, v70
	v_lshlrev_b32_e32 v68, 1, v4
	v_or_b32_e32 v6, 1, v76
	v_lshl_add_u64 v[4:5], s[20:21], 0, v[68:69]
	v_ashrrev_i32_e32 v77, 31, v76
	v_ashrrev_i32_e32 v7, 31, v6
	v_or_b32_e32 v0, s0, v156
	v_lshl_add_u64 v[74:75], v[4:5], 0, s[10:11]
	v_lshlrev_b64 v[4:5], 11, v[76:77]
	v_lshlrev_b64 v[8:9], 11, v[6:7]
	s_lshl_b32 s20, s34, 8
	s_mov_b64 s[14:15], s[56:57]
	v_ashrrev_i32_e32 v1, 31, v0
	v_lshl_add_u64 v[4:5], v[74:75], 0, v[4:5]
	v_lshl_add_u64 v[8:9], v[74:75], 0, v[8:9]
	s_or_b32 s34, s20, s38
	v_lshlrev_b64 v[0:1], 11, v[0:1]
	v_or_b32_e32 v4, 2, v76
	v_or_b32_e32 v32, 3, v76
	s_ashr_i32 s35, s34, 31
	v_lshl_add_u64 v[2:3], s[22:23], 0, v[0:1]
	s_lshl_b32 s8, s38, 8
	v_lshl_add_u64 v[0:1], s[18:19], 0, v[0:1]
	v_ashrrev_i32_e32 v5, 31, v4
	v_ashrrev_i32_e32 v33, 31, v32
	s_lshl_b64 s[20:21], s[34:35], 6
	v_lshl_add_u64 v[0:1], v[0:1], 0, s[8:9]
	v_lshlrev_b64 v[8:9], 11, v[4:5]
	v_lshlrev_b64 v[10:11], 11, v[32:33]
	s_add_u32 s20, s20, s7
	v_lshl_add_u64 v[2:3], v[2:3], 0, s[8:9]
	v_lshl_add_u64 v[0:1], v[0:1], 0, v[72:73]
	v_lshl_add_u64 v[8:9], v[74:75], 0, v[8:9]
	v_lshl_add_u64 v[10:11], v[74:75], 0, v[10:11]
	s_addc_u32 s21, s21, 0
	v_lshl_add_u64 v[2:3], v[2:3], 0, v[72:73]
	v_mov_b32_e32 v1, s21
	v_or_b32_e32 v0, s20, v156
	s_lshl_b64 s[20:21], s[34:35], 7
	s_lshl_b32 s35, s40, 4
	s_add_u32 s20, s20, s35
	s_addc_u32 s21, s21, 0
	v_lshlrev_b64 v[0:1], 7, v[0:1]
	v_mov_b32_e32 v3, s21
	v_or_b32_e32 v2, s20, v156
	v_lshl_add_u64 v[0:1], s[30:31], 0, v[0:1]
	v_lshlrev_b64 v[2:3], 7, v[2:3]
	s_lshl_b32 s43, s38, 2
	v_lshl_add_u64 v[0:1], v[0:1], 0, v[72:73]
	v_lshl_add_u64 v[2:3], s[28:29], 0, v[2:3]
	s_add_u32 s20, s39, s43
	v_lshl_add_u64 v[2:3], v[2:3], 0, v[72:73]
	s_addc_u32 s21, s42, 0
	v_lshlrev_b64 v[0:1], 5, v[76:77]
	v_lshl_add_u64 v[0:1], s[20:21], 0, v[0:1]
	v_lshlrev_b64 v[0:1], 5, v[6:7]
	v_lshl_add_u64 v[0:1], s[20:21], 0, v[0:1]
	v_lshlrev_b64 v[0:1], 5, v[4:5]
	s_or_b32 s40, s16, 63
	v_lshl_add_u64 v[0:1], s[20:21], 0, v[0:1]
	s_ashr_i32 s41, s40, 31
	v_lshlrev_b64 v[0:1], 5, v[32:33]
	s_lshl_b64 s[40:41], s[40:41], 5
	v_lshl_add_u64 v[0:1], s[20:21], 0, v[0:1]
	s_add_u32 s40, s39, s40
	s_addc_u32 s41, s42, s41
	v_mov_b32_e32 v2, s43
	s_add_u32 s22, s22, s8
	s_addc_u32 s23, s23, 0
	v_mul_u32_u24_e32 v32, 0x48, v34
	s_add_u32 s18, s18, s8
	v_lshlrev_b32_e32 v32, 1, v32
	s_addc_u32 s19, s19, 0
	s_lshl_b32 s8, s7, 1
	v_add_u32_e32 v106, 0, v32
	v_add3_u32 v101, v106, s8, v98
	v_add3_u32 v100, v92, s8, v32
	s_lshl_b32 s8, s38, 5
	s_waitcnt lgkmcnt(0)
; #define LAS __attribute__((address_space(3)))
; __device__ __forceinline__ float bf2f(unsigned short b) { return __uint_as_float((unsigned)b << 16); }
; __device__ __forceinline__ void scan_load(ScanFrag& f, int n, int b, int h, int ti, int s, int li, int lq, int ucol, const bf16* Qg, const bf16* Kg, const bf16* Vg, const bf16* KT, const bf16* QK, const float* GC) {
;     const int gcid = b * 32 + n, m0 = b * 2048 + n * 64;
;     const bf16* wrow = Kg + (size_t)(m0 + 16 * ti + li) * D + h * 128 + 8 * lq; const bf16* qrow = Qg + (size_t)(m0 + 16 * ti + li) * D + h * 128 + 8 * lq;
; #pragma unroll
;     for (int ks = 0; ks < 4; ++ks) { f.wA[ks] = *(const bf16x8*)(wrow + 32 * ks); f.qA[ks] = *(const bf16x8*)(qrow + 32 * ks); }
;     const bf16* qkrow = QK + ((size_t)(gcid * 8 + h) * 64 + 16 * ti + li) * 64 + 8 * lq; const bf16* ktrow = KT + ((size_t)(gcid * 8 + h) * 128 + 16 * s + li) * 64 + 8 * lq;
; #pragma unroll
;     for (int k2 = 0; k2 < 2; ++k2) { f.qkA[k2] = *(const bf16x8*)(qkrow + 32 * k2); f.kA[k2] = *(const bf16x8*)(ktrow + 32 * k2); }
;     const int rowb = m0 + 16 * ti + 4 * lq;
; #pragma unroll
;     for (int r = 0; r < 4; ++r) { f.uval[r] = bf2f(Vg[(size_t)(rowb + r) * D + ucol]); f.gcr[r] = GC[(size_t)(rowb + r) * 8 + h]; }
;     f.gl = GC[(size_t)(m0 + 63) * 8 + h];
; }
; __device__ __forceinline__ void scan_unit(LAS unsigned char* lds, int uidx, const bf16* Qg, const bf16* Kg, bf16* Vg, const bf16* KT, const bf16* QK, const float* GC, float* SSQ, float* sp_gdn) {
;     const int tid = threadIdx.x, lane = tid & 63, s = __builtin_amdgcn_readfirstlane(tid >> 6);
;     const int xc = uidx & 7, yy = uidx >> 3, slab = yy & 3, bh = xc * 8 + (yy >> 2), b = bh >> 3, h = bh & 7;
;     LAS bf16* St = (LAS bf16*)lds; LAS bf16* Vt = St + 2 * 32 * 136; LAS bf16* Vts = Vt + 32 * 72;
;     const int ti = s >> 1, c = s & 1, li = lane & 15, lq = lane >> 4;
;     f32x4 S0 = (f32x4){0.f, 0.f, 0.f, 0.f}, S1 = S0;
;     const int ucol = h * 128 + slab * 32 + 16 * c + li;
;     ScanFrag cur, nxt;
;     scan_load(cur, 0, b, h, ti, s, li, lq, ucol, Qg, Kg, Vg, KT, QK, GC);
	s_add_u32 s8, s26, s8
	v_lshl_add_u64 v[80:81], s[18:19], 0, v[72:73]
	s_addc_u32 s18, s27, 0
	s_lshl_b32 s1, s1, 3
	s_add_u32 s1, s8, s1
	s_addc_u32 s8, s18, 0
	s_lshl_b32 s17, s17, 2
	s_add_u32 s1, s1, s17
	s_addc_u32 s8, s8, 0
	s_add_u32 s18, s1, 0xefb6000
	s_addc_u32 s19, s8, 0
	s_ashr_i32 s17, s16, 31
	s_lshl_b64 s[26:27], s[16:17], 5
	s_load_dwordx2 s[14:15], s[14:15], 0x100
	v_lshl_add_u64 v[78:79], s[22:23], 0, v[72:73]
	s_or_b32 s22, s34, 8
	s_or_b32 s1, s26, s43
	v_or_b32_e32 v0, s7, v156
	v_mov_b32_e32 v1, v71
	s_add_u32 s1, s24, s1
	v_lshl_add_u64 v[2:3], s[30:31], 0, v[72:73]
	v_or_b32_e32 v4, s35, v156
	v_mov_b32_e32 v5, v71
	v_lshlrev_b64 v[0:1], 7, v[0:1]
	s_addc_u32 s8, s25, s27
	v_lshl_add_u64 v[6:7], s[28:29], 0, v[72:73]
	v_lshl_add_u64 v[82:83], v[2:3], 0, v[0:1]
	v_lshlrev_b64 v[0:1], 7, v[4:5]
	s_add_u32 s24, s1, 0xef34fe0
	v_mul_u32_u24_e32 v105, 0x110, v34
	v_lshl_add_u64 v[84:85], v[6:7], 0, v[0:1]
	s_addc_u32 s25, s8, 0
	v_add_u32_e32 v107, s0, v97
	s_mov_b32 s8, 0
	s_mov_b32 s17, 0
	v_mov_b32_e32 v4, 0
	v_mov_b32_e32 v5, v69
	v_mov_b32_e32 v6, v69
	v_mov_b32_e32 v7, v69
	v_mov_b32_e32 v0, 0
	v_mov_b32_e32 v1, v69
	v_mov_b32_e32 v2, v69
	v_mov_b32_e32 v3, v69
	s_and_b32 s0, s36, 7
	s_bfe_u32 s1, s36, 0x30005
	s_bfe_u32 s22, s36, 0x20003
	s_lshl_b32 s38, s0, 22
	s_lshl_b32 s39, s1, 8
	s_add_u32 s38, s38, s39
	s_add_u32 s24, s86, 0x6c30000
	s_addc_u32 s25, s87, 0
	s_add_u32 s24, s24, s38
	s_addc_u32 s25, s25, 0
	s_add_u32 s26, s86, 0x4bb0000
	s_addc_u32 s27, s87, 0
	s_add_u32 s26, s26, s38
	s_addc_u32 s27, s27, 0
	s_lshl_b32 s39, s22, 6
	s_add_u32 s98, s86, 0x8cb0000
	s_addc_u32 s99, s87, 0
	s_add_u32 s98, s98, s38
	s_addc_u32 s99, s99, 0
	s_add_u32 s98, s98, s39
	s_addc_u32 s99, s99, 0
	s_lshl_b32 s39, s0, 8
	s_add_u32 s39, s39, s1
	s_lshl_b32 s40, s39, 14
	s_add_u32 s28, s86, 0xad30000
	s_addc_u32 s29, s87, 0
	s_add_u32 s28, s28, s40
	s_addc_u32 s29, s29, 0
	s_lshl_b32 s40, s39, 13
	s_add_u32 s30, s86, 0xcdb0000
	s_addc_u32 s31, s87, 0
	s_add_u32 s30, s30, s40
	s_addc_u32 s31, s31, 0
	s_lshl_b32 s40, s0, 16
	s_lshl_b32 s41, s1, 2
	s_add_u32 s40, s40, s41
	s_add_u32 s100, s86, 0xef34000
	s_addc_u32 s101, s87, 0
	s_add_u32 s100, s100, s40
	s_addc_u32 s101, s101, 0
	v_lshrrev_b32_e32 v176, 4, v154
	v_and_b32_e32 v177, 15, v154
	v_lshlrev_b32_e32 v177, 4, v177
	v_lshl_add_u32 v41, v176, 11, v177
	v_add_u32_e32 v42, 0x10000, v41
	v_mul_u32_u24_e32 v47, 0x110, v176
	v_add_u32_e32 v47, v47, v177
	v_add_u32_e32 v47, 0x6800, v47
	v_lshlrev_b32_e32 v43, 4, v154
	v_add_u32_e32 v44, 0x2000, v43
	v_lshrrev_b32_e32 v176, 3, v154
	v_and_b32_e32 v177, 7, v154
	v_lshlrev_b32_e32 v177, 4, v177
	v_mul_u32_u24_e32 v48, 0x90, v176
	v_add_u32_e32 v48, v48, v177
	v_add_u32_e32 v48, 0xf000, v48
	v_add_u32_e32 v47, 0x4800, v48
	v_and_b32_e32 v176, 0x7f, v154
	v_lshrrev_b32_e32 v177, 7, v154
	v_lshlrev_b32_e32 v177, 4, v177
	v_mul_u32_u24_e32 v48, 0x90, v176
	v_add_u32_e32 v48, v48, v177
	v_add_u32_e32 v48, 0xf000, v48
	v_bfe_u32 v176, v154, 2, 6
	v_and_b32_e32 v177, 3, v154
	v_lshlrev_b32_e32 v177, 4, v177
	v_lshl_add_u32 v45, v176, 11, v177
	v_mul_u32_u24_e32 v49, 0x50, v176
	v_add_u32_e32 v49, v49, v177
	v_add_u32_e32 v49, 0x15c00, v49
	v_and_b32_e32 v176, 63, v154
	v_lshlrev_b32_e32 v46, 5, v176
	v_lshlrev_b32_e32 v50, 2, v176
	v_add_u32_e32 v50, 0x17000, v50
	v_lshrrev_b32_e32 v176, 7, v154
	v_and_b32_e32 v177, 15, v154
	v_lshl_add_u32 v176, v176, 4, v177
	v_bfe_u32 v178, v154, 4, 2
	v_lshlrev_b32_e32 v179, 4, v178
	v_mul_u32_u24_e32 v51, 0x110, v176
	v_add_u32_e32 v51, v51, v179
	v_add_u32_e32 v51, 0x6800, v51
	v_mul_u32_u24_e32 v52, 0x90, v176
	v_add_u32_e32 v52, v52, v179
	v_add_u32_e32 v52, 0x13800, v52
	v_lshrrev_b32_e32 v180, 6, v154
	v_lshl_add_u32 v180, v180, 4, v177
	v_mul_u32_u24_e32 v53, 0x90, v180
	v_add_u32_e32 v53, v53, v179
	v_add_u32_e32 v53, 0xf000, v53
	v_lshrrev_b32_e32 v180, 7, v154
	v_lshlrev_b32_e32 v180, 4, v180
	v_lshl_add_u32 v180, v178, 2, v180
	v_mul_u32_u24_e32 v54, 0x50, v180
	v_bfe_u32 v181, v154, 6, 1
	v_lshl_add_u32 v181, v181, 4, v177
	v_lshl_add_u32 v54, v181, 1, v54
	v_add_u32_e32 v54, 0x15c00, v54
	v_lshlrev_b32_e32 v55, 2, v180
	v_add_u32_e32 v55, 0x17000, v55
	v_mov_b32_e32 v174, 0x170fc
	v_lshrrev_b32_e32 v176, 7, v154
	v_bfe_u32 v178, v154, 4, 2
	v_lshl_add_u32 v176, v176, 4, v178
	v_and_b32_e32 v177, 15, v154
	v_lshlrev_b32_e32 v177, 4, v177
	v_lshl_add_u32 v236, v176, 11, v177
	v_add_u32_e32 v237, 0x2000, v236
	v_add_u32_e32 v238, 0x4000, v236
	v_add_u32_e32 v239, 0x6000, v236
	v_and_b32_e32 v241, 1, v156
	v_mov_b32_e32 v240, 0x5040100
	v_mov_b32_e32 v242, 0x3020706
	v_cmp_eq_u32_e64 s[96:97], 1, v241
	v_and_b32_e32 v241, 3, v156
	s_nop 0
	v_cndmask_b32_e64 v240, v240, v242, s[96:97]
	v_lshlrev_b32_e32 v242, 1, v241
	v_sub_co_u32_e64 v242, s[96:97], v74, v242
	s_nop 1
	v_subb_co_u32_e64 v243, s[96:97], v75, 0, s[96:97]
	global_load_dwordx4 v[8:11], v236, s[24:25]
	global_load_dwordx4 v[12:15], v237, s[24:25]
	global_load_dwordx4 v[16:19], v238, s[24:25]
	global_load_dwordx4 v[20:23], v239, s[24:25]
	global_load_dwordx4 v[130:133], v236, s[26:27]
	global_load_dwordx4 v[134:137], v237, s[26:27]
	global_load_dwordx4 v[138:141], v238, s[26:27]
	global_load_dwordx4 v[142:145], v239, s[26:27]
	s_add_u32 s24, s24, 0x20000
	s_addc_u32 s25, s25, 0
	s_add_u32 s26, s26, 0x20000
	s_addc_u32 s27, s27, 0
	global_load_dwordx4 v[24:27], v43, s[28:29]
	global_load_dwordx4 v[28:31], v44, s[28:29]
	global_load_dwordx4 v[32:35], v43, s[30:31]
	s_cmp_gt_u32 s95, 3
	s_cbranch_scc1 .Lscan_sl1u
	global_load_dwordx4 v[36:39], v45, s[98:99]
.Lscan_sl1u:
	s_cmp_lg_u32 s95, 0
	s_cbranch_scc1 .Lscan_sl1g
	global_load_dword v40, v46, s[100:101]
.Lscan_sl1g:
	s_waitcnt vmcnt(0)
	ds_write_b128 v48, v[24:27]
	ds_write_b128 v48, v[28:31] offset:64
	ds_write_b128 v47, v[32:35]
	s_cmp_gt_u32 s95, 3
	s_cbranch_scc1 .Lscan_sw6u
	ds_write_b128 v49, v[36:39]
.Lscan_sw6u:
	s_cmp_lg_u32 s95, 0
	s_cbranch_scc1 .Lscan_sw6g
	ds_write_b32 v50, v40
.Lscan_sw6g:
	s_add_u32 s28, s28, 0x20000
	s_addc_u32 s29, s29, 0
	s_add_u32 s30, s30, 0x10000
	s_addc_u32 s31, s31, 0
	s_add_u32 s98, s98, 0x20000
	s_addc_u32 s99, s99, 0
	s_add_u32 s100, s100, 0x800
	s_addc_u32 s101, s101, 0
	global_load_dwordx4 v[24:27], v43, s[28:29]
	global_load_dwordx4 v[28:31], v44, s[28:29]
	global_load_dwordx4 v[32:35], v43, s[30:31]
	s_cmp_gt_u32 s95, 3
	s_cbranch_scc1 .Lscan_sl2u
	global_load_dwordx4 v[36:39], v45, s[98:99]

; #define LAS __attribute__((address_space(3)))
; #define LDS_BARRIER() do { asm volatile("s_waitcnt lgkmcnt(0)" ::: "memory"); __builtin_amdgcn_s_barrier(); asm volatile("" ::: "memory"); } while (0)
; __device__ __forceinline__ void scan_unit(LAS unsigned char* lds, int uidx, const bf16* Qg, const bf16* Kg, bf16* Vg, const bf16* KT, const bf16* QK, const float* GC, float* SSQ, float* sp_gdn) {
;     ...
;     for (int n = 0; n < 32; ++n) {
;         const int m0 = b * 2048 + n * 64, rowb = m0 + 16 * ti + 4 * lq;
;         __builtin_amdgcn_sched_barrier(0);
;         if (n + 1 < 32) scan_load(nxt, n + 1, b, h, ti, s, li, lq, ucol, Qg, Kg, Vg, KT, QK, GC);
;         __builtin_amdgcn_sched_barrier(0);
;         const bf16x8 (&wA)[4] = cur.wA; const bf16x8 (&qA)[4] = cur.qA; const bf16x8 (&qkA)[2] = cur.qkA; const bf16x8 (&kA)[2] = cur.kA;
;         const float (&uval)[4] = cur.uval; const float (&gcr)[4] = cur.gcr; const float gl = cur.gl;
;         LAS bf16* Sb = St + (n & 1) * 32 * 136;
;         { u32x2 w; w.x = cvt_pk_bf16(S0[0], S0[1]); w.y = cvt_pk_bf16(S0[2], S0[3]); *(LAS u32x2*)(Sb + li * 136 + 16 * s + 4 * lq) = w;
;           w.x = cvt_pk_bf16(S1[0], S1[1]); w.y = cvt_pk_bf16(S1[2], S1[3]); *(LAS u32x2*)(Sb + (16 + li) * 136 + 16 * s + 4 * lq) = w; }
;         LDS_BARRIER();
;         bf16x8 bS[4]; f32x4 acc = (f32x4){0.f, 0.f, 0.f, 0.f};
; #pragma unroll
;         for (int ks = 0; ks < 4; ++ks) { bS[ks] = *(const LAS bf16x8*)(Sb + (16 * c + li) * 136 + 32 * ks + 8 * lq); acc = __builtin_amdgcn_mfma_f32_16x16x32_bf16(wA[ks], bS[ks], acc, 0, 0, 0); }
;         f32x4 o = (f32x4){0.f, 0.f, 0.f, 0.f};
; #pragma unroll
;         for (int ks = 0; ks < 4; ++ks) o = __builtin_amdgcn_mfma_f32_16x16x32_bf16(qA[ks], bS[ks], o, 0, 0, 0);
;         { float vn[4], vs[4];
; #pragma unroll
;           for (int r = 0; r < 4; ++r) { vn[r] = uval[r] - acc[r]; vs[r] = vn[r] * __expf(gl - gcr[r]); }
;           u32x2 w; w.x = cvt_pk_bf16(vn[0], vn[1]); w.y = cvt_pk_bf16(vn[2], vn[3]); *(LAS u32x2*)(Vt + (16 * c + li) * 72 + 16 * ti + 4 * lq) = w;
;           w.x = cvt_pk_bf16(vs[0], vs[1]); w.y = cvt_pk_bf16(vs[2], vs[3]); *(LAS u32x2*)(Vts + (16 * c + li) * 72 + 16 * ti + 4 * lq) = w; }
;         LDS_BARRIER();
.Lscan_sl2g:
	s_add_u32 s28, s28, 0x20000
	s_addc_u32 s29, s29, 0
	s_add_u32 s30, s30, 0x10000
	s_addc_u32 s31, s31, 0
	s_add_u32 s98, s98, 0x20000
	s_addc_u32 s99, s99, 0
	s_add_u32 s100, s100, 0x800
	s_addc_u32 s101, s101, 0
	global_load_dwordx4 v[200:203], v43, s[28:29]
	global_load_dwordx4 v[204:207], v44, s[28:29]
	global_load_dwordx4 v[208:211], v43, s[30:31]
	s_cmp_gt_u32 s95, 3
	s_cbranch_scc1 .Lscan_sl3u
	global_load_dwordx4 v[212:215], v45, s[98:99]
.Lscan_sl3u:
	s_cmp_lg_u32 s95, 0
	s_cbranch_scc1 .Lscan_sl3g
	global_load_dword v216, v46, s[100:101]
.Lscan_sl3g:
.LBB0_833:
	v_add_u32_e32 v86, s8, v76
	global_load_dwordx4 v[184:187], v236, s[24:25]
	global_load_dwordx4 v[188:191], v237, s[24:25]
	global_load_dwordx4 v[192:195], v238, s[24:25]
	global_load_dwordx4 v[196:199], v239, s[24:25]
	global_load_dwordx4 v[220:223], v236, s[26:27]
	global_load_dwordx4 v[224:227], v237, s[26:27]
	global_load_dwordx4 v[228:231], v238, s[26:27]
	global_load_dwordx4 v[232:235], v239, s[26:27]
	s_add_u32 s24, s24, 0x20000
	s_addc_u32 s25, s25, 0
	s_add_u32 s26, s26, 0x20000
	s_addc_u32 s27, s27, 0
	s_and_b32 s0, s17, 32
	s_mulk_i32 s0, 0x110
	s_add_i32 s0, s0, 0
	s_lshl_b32 s23, s35, 1
	s_add_i32 s1, s23, s0
	v_cvt_pk_bf16_f32 v88, v4, v5
	v_cvt_pk_bf16_f32 v89, v6, v7
	v_add3_u32 v150, s1, v90, v98
	ds_write_b64 v150, v[88:89]
	v_cvt_pk_bf16_f32 v88, v0, v1
	v_cvt_pk_bf16_f32 v89, v2, v3
	v_add3_u32 v150, s1, v91, v98
	ds_write_b64 v150, v[88:89]
	s_waitcnt lgkmcnt(0)
	s_barrier
	v_add3_u32 v88, s0, v105, v94
	ds_read_b128 v[162:165], v88
	ds_read_b128 v[166:169], v88 offset:64
	ds_read_b128 v[176:179], v55
	ds_read_b32 v108, v174
	ds_read_u16 v180, v54
	ds_read_u16 v181, v54 offset:80
	ds_read_u16 v182, v54 offset:160
	ds_read_u16 v183, v54 offset:240
	s_waitcnt lgkmcnt(0)
	s_cmpk_gt_u32 s8, 0x740
	s_cbranch_scc1 .LscanA_fw
	s_waitcnt vmcnt(13)
	s_branch .LscanA_fg
.LscanA_fw:
	s_waitcnt vmcnt(10)
.LscanA_fg:
	v_mov_b32_e32 v87, v176
	v_mov_b32_e32 v110, v177
	v_mov_b32_e32 v153, v178
	v_mov_b32_e32 v155, v179
	v_lshlrev_b32_e32 v66, 16, v180
	v_lshlrev_b32_e32 v67, 16, v181
	v_lshlrev_b32_e32 v64, 16, v182
	v_lshlrev_b32_e32 v65, 16, v183
	v_mfma_f32_16x16x32_bf16 v[114:117], v[8:11], v[162:165], 0
	v_sub_f32_e32 v89, v108, v110
	v_mul_f32_e32 v89, 0x3fb8aa3b, v89
	v_exp_f32_e32 v89, v89
	v_mfma_f32_16x16x32_bf16 v[114:117], v[12:15], v[166:169], v[114:117]
	ds_read_b128 v[118:121], v88 offset:128
	ds_read_b128 v[170:173], v88 offset:192
	ds_read_b128 v[146:149], v52
	ds_read_b128 v[158:161], v52 offset:64
	ds_read_b128 v[60:63], v53
	ds_read_b128 v[56:59], v53 offset:64
	v_sub_f32_e32 v88, v108, v87
	v_mul_f32_e32 v88, 0x3fb8aa3b, v88
	s_waitcnt lgkmcnt(5)
	v_mfma_f32_16x16x32_bf16 v[114:117], v[16:19], v[118:121], v[114:117]
	v_exp_f32_e32 v88, v88
	s_waitcnt lgkmcnt(4)
	v_mfma_f32_16x16x32_bf16 v[122:125], v[130:133], v[162:165], 0
	v_mfma_f32_16x16x32_bf16 v[114:117], v[20:23], v[170:173], v[114:117]
	v_sub_f32_e32 v126, v108, v153
	v_sub_f32_e32 v127, v108, v155
	v_mul_f32_e32 v126, 0x3fb8aa3b, v126
	v_mul_f32_e32 v127, 0x3fb8aa3b, v127
	v_exp_f32_e32 v126, v126
	v_exp_f32_e32 v127, v127
	v_mfma_f32_16x16x32_bf16 v[122:125], v[134:137], v[166:169], v[122:125]
	s_nop 0
	v_add_f32_e64 v66, v66, -v114
	v_add_f32_e64 v67, v67, -v115
	v_pk_add_f32 v[64:65], v[64:65], v[116:117] neg_lo:[0,1] neg_hi:[0,1]
	v_pk_mul_f32 v[88:89], v[88:89], v[66:67]
	v_pk_mul_f32 v[114:115], v[126:127], v[64:65]
	v_mfma_f32_16x16x32_bf16 v[118:121], v[138:141], v[118:121], v[122:125]
	v_cvt_pk_bf16_f32 v66, v66, v67
	v_cvt_pk_bf16_f32 v88, v88, v89
	v_cvt_pk_bf16_f32 v67, v64, v65
	v_cvt_pk_bf16_f32 v89, v114, v115
	v_mul_f32_e32 v64, 0x3fb8aa3b, v87
	ds_write_b64 v100, v[88:89] offset:22016
	v_exp_f32_e32 v88, v64
	v_mul_f32_e32 v64, 0x3fb8aa3b, v110
	ds_write_b64 v101, v[66:67] offset:17408
	v_exp_f32_e32 v89, v64
	v_mul_f32_e32 v64, 0x3fb8aa3b, v153
	s_waitcnt lgkmcnt(0)
	s_barrier
; #define LAS __attribute__((address_space(3)))
; __device__ __forceinline__ unsigned short f2bf(float f) { return (unsigned short)(cvt_pk_bf16(f, 0.f) & 0xffffu); }
; __device__ __forceinline__ void scan_unit(LAS unsigned char* lds, int uidx, const bf16* Qg, const bf16* Kg, bf16* Vg, const bf16* KT, const bf16* QK, const float* GC, float* SSQ, float* sp_gdn) {
;     ...
; #pragma unroll
;         for (int r = 0; r < 4; ++r) o[r] *= __expf(gcr[r]);
; #pragma unroll
;         for (int k2 = 0; k2 < 2; ++k2) { const bf16x8 bV = *(const LAS bf16x8*)(Vt + (16 * c + li) * 72 + 32 * k2 + 8 * lq); o = __builtin_amdgcn_mfma_f32_16x16x32_bf16(qkA[k2], bV, o, 0, 0, 0); }
; #pragma unroll
;         for (int r = 0; r < 4; ++r) { Vg[(size_t)(rowb + r) * D + ucol] = f2bf(o[r]); const float sq = row16_sum(o[r] * o[r]);
;             if (li == 0) SSQ[((size_t)(rowb + r) * 8 + h) * 8 + slab * 2 + c] = sq; }
;         const float eg = __expf(gl); S0 = S0 * eg; S1 = S1 * eg;
; #pragma unroll
;         for (int k2 = 0; k2 < 2; ++k2) { const bf16x8 b0 = *(const LAS bf16x8*)(Vts + li * 72 + 32 * k2 + 8 * lq), b1 = *(const LAS bf16x8*)(Vts + (16 + li) * 72 + 32 * k2 + 8 * lq);
;             S0 = __builtin_amdgcn_mfma_f32_16x16x32_bf16(kA[k2], b0, S0, 0, 0, 0); S1 = __builtin_amdgcn_mfma_f32_16x16x32_bf16(kA[k2], b1, S1, 0, 0, 0); }
	v_exp_f32_e32 v122, v64
	v_mul_f32_e32 v64, 0x3fb8aa3b, v155
	v_add_u32_e32 v110, v106, v94
	v_exp_f32_e32 v123, v64
	ds_read_b128 v[64:67], v110 offset:17408
	v_mfma_f32_16x16x32_bf16 v[114:117], v[142:145], v[170:173], v[118:121]
	v_ashrrev_i32_e32 v87, 31, v86
	s_nop 1
	ds_read_b128 v[118:121], v110 offset:17472
	s_nop 3
	v_pk_mul_f32 v[114:115], v[88:89], v[114:115]
	v_pk_mul_f32 v[116:117], v[122:123], v[116:117]
	v_lshlrev_b64 v[88:89], 11, v[86:87]
	v_lshl_add_u64 v[88:89], v[74:75], 0, v[88:89]
	s_waitcnt lgkmcnt(1)
	v_mfma_f32_16x16x32_bf16 v[64:67], v[146:149], v[64:67], v[114:117]
	s_waitcnt lgkmcnt(0)
	v_mfma_f32_16x16x32_bf16 v[64:67], v[158:161], v[118:121], v[64:67]
	s_nop 7
	v_mul_f32_e32 v114, v64, v64
	v_mul_f32_e32 v115, v65, v65
	v_mul_f32_e32 v116, v66, v66
	v_mul_f32_e32 v117, v67, v67
	v_mov_b32_dpp v114, v114 row_ror:8 row_mask:0xf bank_mask:0xf bound_ctrl:1
	v_mov_b32_dpp v115, v115 row_ror:8 row_mask:0xf bank_mask:0xf bound_ctrl:1
	v_mov_b32_dpp v116, v116 row_ror:8 row_mask:0xf bank_mask:0xf bound_ctrl:1
	v_mov_b32_dpp v117, v117 row_ror:8 row_mask:0xf bank_mask:0xf bound_ctrl:1
	v_fmac_f32_e32 v114, v64, v64
	v_fmac_f32_e32 v115, v65, v65
	v_fmac_f32_e32 v116, v66, v66
	v_fmac_f32_e32 v117, v67, v67
	v_add_f32_dpp v118, v114, v114 row_ror:4 row_mask:0xf bank_mask:0xf bound_ctrl:1
	v_add_f32_dpp v119, v115, v115 row_ror:4 row_mask:0xf bank_mask:0xf bound_ctrl:1
	v_add_f32_dpp v120, v116, v116 row_ror:4 row_mask:0xf bank_mask:0xf bound_ctrl:1
	v_add_f32_dpp v121, v117, v117 row_ror:4 row_mask:0xf bank_mask:0xf bound_ctrl:1
	v_add_f32_dpp v118, v118, v118 row_ror:2 row_mask:0xf bank_mask:0xf bound_ctrl:1
	v_add_f32_dpp v119, v119, v119 row_ror:2 row_mask:0xf bank_mask:0xf bound_ctrl:1
	v_add_f32_dpp v120, v120, v120 row_ror:2 row_mask:0xf bank_mask:0xf bound_ctrl:1
	v_add_f32_dpp v121, v121, v121 row_ror:2 row_mask:0xf bank_mask:0xf bound_ctrl:1
	v_mov_b32_dpp v114, v118 row_ror:1 row_mask:0xf bank_mask:0xf bound_ctrl:1
	v_mov_b32_dpp v115, v119 row_ror:1 row_mask:0xf bank_mask:0xf bound_ctrl:1
	v_mov_b32_dpp v116, v120 row_ror:1 row_mask:0xf bank_mask:0xf bound_ctrl:1
	v_mov_b32_dpp v117, v121 row_ror:1 row_mask:0xf bank_mask:0xf bound_ctrl:1
	v_add_f32_e32 v118, v118, v114
	v_add_f32_e32 v119, v119, v115
	v_add_f32_e32 v120, v120, v116
	v_add_f32_e32 v121, v121, v117
	v_cvt_pk_bf16_f32 v114, v64, v65
	v_cvt_pk_bf16_f32 v115, v66, v67
	v_mov_b32_dpp v119, v119 quad_perm:[0,0,0,0] row_mask:0xf bank_mask:0xf bound_ctrl:1
	v_mov_b32_dpp v120, v120 quad_perm:[0,0,0,0] row_mask:0xf bank_mask:0xf bound_ctrl:1
	v_mov_b32_dpp v121, v121 quad_perm:[0,0,0,0] row_mask:0xf bank_mask:0xf bound_ctrl:1
	v_mov_b32_dpp v116, v114 quad_perm:[2,3,0,1] row_mask:0xf bank_mask:0xf bound_ctrl:1
	v_mov_b32_dpp v117, v115 quad_perm:[2,3,0,1] row_mask:0xf bank_mask:0xf bound_ctrl:1
	v_cmp_eq_u32_e64 s[96:97], 1, v156
	v_cmp_eq_u32_e64 s[0:1], 2, v156
	v_and_b32_e32 v88, 2, v156
	v_cndmask_b32_e64 v118, v118, v119, s[96:97]
	v_cmp_eq_u32_e64 s[96:97], 3, v156
	v_cndmask_b32_e64 v118, v118, v120, s[0:1]
	v_cmp_ne_u32_e64 s[0:1], 0, v88
	v_cndmask_b32_e64 v118, v118, v121, s[96:97]
	v_add_u32_e32 v120, v86, v156
	v_mov_b32_e32 v121, 0
	v_cndmask_b32_e64 v114, v114, v117, s[0:1]
	v_cndmask_b32_e64 v115, v116, v115, s[0:1]
	v_lshlrev_b64 v[120:121], 8, v[120:121]
	v_add_u32_e32 v88, v86, v241
	v_mov_b32_dpp v116, v114 quad_perm:[1,0,3,2] row_mask:0xf bank_mask:0xf bound_ctrl:1
	v_mov_b32_dpp v117, v115 quad_perm:[1,0,3,2] row_mask:0xf bank_mask:0xf bound_ctrl:1
	v_lshl_add_u64 v[120:121], s[18:19], 0, v[120:121]
	v_mov_b32_e32 v89, 0
	v_perm_b32 v114, v116, v114, v240
	v_perm_b32 v115, v117, v115, v240
	v_lshlrev_b64 v[88:89], 11, v[88:89]
	v_cmp_gt_u32_e64 s[96:97], 4, v156
	v_lshl_add_u64 v[88:89], v[242:243], 0, v[88:89]
	global_store_dwordx2 v[88:89], v[114:115], off
	s_and_saveexec_b64 s[0:1], s[96:97]
	global_store_dword v[120:121], v118, off
	s_or_b64 exec, exec, s[0:1]
	v_mul_f32_e32 v64, 0x3fb8aa3b, v108
	v_exp_f32_e32 v108, v64
	ds_read_b128 v[64:67], v99 offset:22016
	ds_read_b128 v[86:89], v99 offset:24320
	ds_read_b128 v[114:117], v99 offset:22080
	ds_read_b128 v[118:121], v99 offset:24384
	v_pk_mul_f32 v[6:7], v[6:7], v[108:109] op_sel_hi:[1,0]
	v_pk_mul_f32 v[4:5], v[4:5], v[108:109] op_sel_hi:[1,0]
	v_pk_mul_f32 v[2:3], v[2:3], v[108:109] op_sel_hi:[1,0]
	v_pk_mul_f32 v[0:1], v[0:1], v[108:109] op_sel_hi:[1,0]
	s_waitcnt lgkmcnt(3)
	v_mfma_f32_16x16x32_bf16 v[4:7], v[60:63], v[64:67], v[4:7]
	s_waitcnt lgkmcnt(2)
	v_mfma_f32_16x16x32_bf16 v[0:3], v[60:63], v[86:89], v[0:3]
	s_waitcnt lgkmcnt(1)
	v_mfma_f32_16x16x32_bf16 v[4:7], v[56:59], v[114:117], v[4:7]
	s_waitcnt lgkmcnt(0)
	v_mfma_f32_16x16x32_bf16 v[0:3], v[56:59], v[118:121], v[0:3]
	s_cmpk_gt_u32 s8, 0x780
	s_cbranch_scc1 .LscanA_nostage
	s_cmpk_gt_u32 s8, 0x700
	s_cbranch_scc1 .LscanA_strict
	s_waitcnt vmcnt(13)
	s_branch .LscanA_wr
.LscanA_strict:
	s_waitcnt vmcnt(13)
.LscanA_wr:
	ds_write_b128 v48, v[24:27]
	ds_write_b128 v48, v[28:31] offset:64
	ds_write_b128 v47, v[32:35]
	s_cmp_gt_u32 s95, 3
	s_cbranch_scc1 .Lscan_sw7u
	ds_write_b128 v49, v[36:39]

; __device__ __forceinline__ float bf2f(unsigned short b) { return __uint_as_float((unsigned)b << 16); }
; __device__ __forceinline__ void scan_load(ScanFrag& f, int n, int b, int h, int ti, int s, int li, int lq, int ucol, const bf16* Qg, const bf16* Kg, const bf16* Vg, const bf16* KT, const bf16* QK, const float* GC) {
;     const int gcid = b * 32 + n, m0 = b * 2048 + n * 64;
;     const bf16* wrow = Kg + (size_t)(m0 + 16 * ti + li) * D + h * 128 + 8 * lq; const bf16* qrow = Qg + (size_t)(m0 + 16 * ti + li) * D + h * 128 + 8 * lq;
; #pragma unroll
;     for (int ks = 0; ks < 4; ++ks) { f.wA[ks] = *(const bf16x8*)(wrow + 32 * ks); f.qA[ks] = *(const bf16x8*)(qrow + 32 * ks); }
;     const bf16* qkrow = QK + ((size_t)(gcid * 8 + h) * 64 + 16 * ti + li) * 64 + 8 * lq; const bf16* ktrow = KT + ((size_t)(gcid * 8 + h) * 128 + 16 * s + li) * 64 + 8 * lq;
; #pragma unroll
;     for (int k2 = 0; k2 < 2; ++k2) { f.qkA[k2] = *(const bf16x8*)(qkrow + 32 * k2); f.kA[k2] = *(const bf16x8*)(ktrow + 32 * k2); }
;     const int rowb = m0 + 16 * ti + 4 * lq;
; #pragma unroll
;     for (int r = 0; r < 4; ++r) { f.uval[r] = bf2f(Vg[(size_t)(rowb + r) * D + ucol]); f.gcr[r] = GC[(size_t)(rowb + r) * 8 + h]; }
;     f.gl = GC[(size_t)(m0 + 63) * 8 + h];
.Lscan_sw7g:
	s_cmpk_gt_u32 s8, 0x700
	s_cbranch_scc1 .LscanA_nostage
	s_add_u32 s28, s28, 0x20000
	s_addc_u32 s29, s29, 0
	s_add_u32 s30, s30, 0x10000
	s_addc_u32 s31, s31, 0
	s_add_u32 s98, s98, 0x20000
	s_addc_u32 s99, s99, 0
	s_add_u32 s100, s100, 0x800
	s_addc_u32 s101, s101, 0
	global_load_dwordx4 v[24:27], v43, s[28:29]
	global_load_dwordx4 v[28:31], v44, s[28:29]
	global_load_dwordx4 v[32:35], v43, s[30:31]
	s_cmp_gt_u32 s95, 3
	s_cbranch_scc1 .Lscan_sl4u
	global_load_dwordx4 v[36:39], v45, s[98:99]

; __device__ __forceinline__ void scan_unit(LAS unsigned char* lds, int uidx, const bf16* Qg, const bf16* Kg, bf16* Vg, const bf16* KT, const bf16* QK, const float* GC, float* SSQ, float* sp_gdn) {
;     ...
;     for (int n = 0; n < 32; ++n) {
;         const int m0 = b * 2048 + n * 64, rowb = m0 + 16 * ti + 4 * lq;
;         __builtin_amdgcn_sched_barrier(0);
;         if (n + 1 < 32) scan_load(nxt, n + 1, b, h, ti, s, li, lq, ucol, Qg, Kg, Vg, KT, QK, GC);
;         __builtin_amdgcn_sched_barrier(0);
;     ...
;         __builtin_amdgcn_sched_barrier(0);
;         cur = nxt;
;     }
.Lscan_sl4g:
.LscanA_nostage:
	s_add_i32 s17, s17, 32
	s_add_i32 s8, s8, 64

; #define LAS __attribute__((address_space(3)))
; #define LDS_BARRIER() do { asm volatile("s_waitcnt lgkmcnt(0)" ::: "memory"); __builtin_amdgcn_s_barrier(); asm volatile("" ::: "memory"); } while (0)
; __device__ __forceinline__ void scan_unit(LAS unsigned char* lds, int uidx, const bf16* Qg, const bf16* Kg, bf16* Vg, const bf16* KT, const bf16* QK, const float* GC, float* SSQ, float* sp_gdn) {
;     ...
;         LAS bf16* Sb = St + (n & 1) * 32 * 136;
;         { u32x2 w; w.x = cvt_pk_bf16(S0[0], S0[1]); w.y = cvt_pk_bf16(S0[2], S0[3]); *(LAS u32x2*)(Sb + li * 136 + 16 * s + 4 * lq) = w;
;           w.x = cvt_pk_bf16(S1[0], S1[1]); w.y = cvt_pk_bf16(S1[2], S1[3]); *(LAS u32x2*)(Sb + (16 + li) * 136 + 16 * s + 4 * lq) = w; }
;         LDS_BARRIER();
;         bf16x8 bS[4]; f32x4 acc = (f32x4){0.f, 0.f, 0.f, 0.f};
; #pragma unroll
;         for (int ks = 0; ks < 4; ++ks) { bS[ks] = *(const LAS bf16x8*)(Sb + (16 * c + li) * 136 + 32 * ks + 8 * lq); acc = __builtin_amdgcn_mfma_f32_16x16x32_bf16(wA[ks], bS[ks], acc, 0, 0, 0); }
.LscanB_nodir:
	s_and_b32 s0, s17, 32
	s_mulk_i32 s0, 0x110
	s_add_i32 s0, s0, 0
	s_lshl_b32 s23, s35, 1
	s_add_i32 s1, s23, s0
	v_cvt_pk_bf16_f32 v88, v4, v5
	v_cvt_pk_bf16_f32 v89, v6, v7
	v_add3_u32 v150, s1, v90, v98
	ds_write_b64 v150, v[88:89]
	v_cvt_pk_bf16_f32 v88, v0, v1
	v_cvt_pk_bf16_f32 v89, v2, v3
	v_add3_u32 v150, s1, v91, v98
	ds_write_b64 v150, v[88:89]
	s_waitcnt lgkmcnt(0)
	s_barrier
	v_add3_u32 v88, s0, v105, v94
	ds_read_b128 v[162:165], v88
	ds_read_b128 v[166:169], v88 offset:64
	ds_read_b128 v[176:179], v55
	ds_read_b32 v108, v174
	ds_read_u16 v180, v54
	ds_read_u16 v181, v54 offset:80
	ds_read_u16 v182, v54 offset:160
	ds_read_u16 v183, v54 offset:240
	s_waitcnt lgkmcnt(0)
	s_cmpk_gt_u32 s8, 0x780
	s_cbranch_scc1 .LscanB_fw
	s_waitcnt vmcnt(13)
	s_branch .LscanB_fg
.LscanB_fw:
	s_waitcnt vmcnt(2)
; #define LAS __attribute__((address_space(3)))
; __device__ __forceinline__ unsigned short f2bf(float f) { return (unsigned short)(cvt_pk_bf16(f, 0.f) & 0xffffu); }
; __device__ __forceinline__ void scan_unit(LAS unsigned char* lds, int uidx, const bf16* Qg, const bf16* Kg, bf16* Vg, const bf16* KT, const bf16* QK, const float* GC, float* SSQ, float* sp_gdn) {
;     ...
;         bf16x8 bS[4]; f32x4 acc = (f32x4){0.f, 0.f, 0.f, 0.f};
; #pragma unroll
;         for (int ks = 0; ks < 4; ++ks) { bS[ks] = *(const LAS bf16x8*)(Sb + (16 * c + li) * 136 + 32 * ks + 8 * lq); acc = __builtin_amdgcn_mfma_f32_16x16x32_bf16(wA[ks], bS[ks], acc, 0, 0, 0); }
;         f32x4 o = (f32x4){0.f, 0.f, 0.f, 0.f};
; #pragma unroll
;         for (int ks = 0; ks < 4; ++ks) o = __builtin_amdgcn_mfma_f32_16x16x32_bf16(qA[ks], bS[ks], o, 0, 0, 0);
;         { float vn[4], vs[4];
; #pragma unroll
;           for (int r = 0; r < 4; ++r) { vn[r] = uval[r] - acc[r]; vs[r] = vn[r] * __expf(gl - gcr[r]); }
;           u32x2 w; w.x = cvt_pk_bf16(vn[0], vn[1]); w.y = cvt_pk_bf16(vn[2], vn[3]); *(LAS u32x2*)(Vt + (16 * c + li) * 72 + 16 * ti + 4 * lq) = w;
;           w.x = cvt_pk_bf16(vs[0], vs[1]); w.y = cvt_pk_bf16(vs[2], vs[3]); *(LAS u32x2*)(Vts + (16 * c + li) * 72 + 16 * ti + 4 * lq) = w; }
;         LDS_BARRIER();
; #pragma unroll
;         for (int r = 0; r < 4; ++r) o[r] *= __expf(gcr[r]);
; #pragma unroll
;         for (int k2 = 0; k2 < 2; ++k2) { const bf16x8 bV = *(const LAS bf16x8*)(Vt + (16 * c + li) * 72 + 32 * k2 + 8 * lq); o = __builtin_amdgcn_mfma_f32_16x16x32_bf16(qkA[k2], bV, o, 0, 0, 0); }
; #pragma unroll
;         for (int r = 0; r < 4; ++r) { Vg[(size_t)(rowb + r) * D + ucol] = f2bf(o[r]); const float sq = row16_sum(o[r] * o[r]);
;             if (li == 0) SSQ[((size_t)(rowb + r) * 8 + h) * 8 + slab * 2 + c] = sq; }
;         const float eg = __expf(gl); S0 = S0 * eg; S1 = S1 * eg;
; #pragma unroll
;         for (int k2 = 0; k2 < 2; ++k2) { const bf16x8 b0 = *(const LAS bf16x8*)(Vts + li * 72 + 32 * k2 + 8 * lq), b1 = *(const LAS bf16x8*)(Vts + (16 + li) * 72 + 32 * k2 + 8 * lq);
;             S0 = __builtin_amdgcn_mfma_f32_16x16x32_bf16(kA[k2], b0, S0, 0, 0, 0); S1 = __builtin_amdgcn_mfma_f32_16x16x32_bf16(kA[k2], b1, S1, 0, 0, 0); }
.LscanB_fg:
	v_mov_b32_e32 v87, v176
	v_mov_b32_e32 v110, v177
	v_mov_b32_e32 v153, v178
	v_mov_b32_e32 v155, v179
	v_lshlrev_b32_e32 v66, 16, v180
	v_lshlrev_b32_e32 v67, 16, v181
	v_lshlrev_b32_e32 v64, 16, v182
	v_lshlrev_b32_e32 v65, 16, v183
	v_mfma_f32_16x16x32_bf16 v[114:117], v[184:187], v[162:165], 0
	v_sub_f32_e32 v89, v108, v110
	v_mul_f32_e32 v89, 0x3fb8aa3b, v89
	v_exp_f32_e32 v89, v89
	v_mfma_f32_16x16x32_bf16 v[114:117], v[188:191], v[166:169], v[114:117]
	ds_read_b128 v[118:121], v88 offset:128
	ds_read_b128 v[170:173], v88 offset:192
	ds_read_b128 v[146:149], v52
	ds_read_b128 v[158:161], v52 offset:64
	ds_read_b128 v[60:63], v53
	ds_read_b128 v[56:59], v53 offset:64
	v_sub_f32_e32 v88, v108, v87
	v_mul_f32_e32 v88, 0x3fb8aa3b, v88
	s_waitcnt lgkmcnt(5)
	v_mfma_f32_16x16x32_bf16 v[114:117], v[192:195], v[118:121], v[114:117]
	v_exp_f32_e32 v88, v88
	s_waitcnt lgkmcnt(4)
	v_mfma_f32_16x16x32_bf16 v[122:125], v[220:223], v[162:165], 0
	v_mfma_f32_16x16x32_bf16 v[114:117], v[196:199], v[170:173], v[114:117]
	v_sub_f32_e32 v126, v108, v153
	v_sub_f32_e32 v127, v108, v155
	v_mul_f32_e32 v126, 0x3fb8aa3b, v126
	v_mul_f32_e32 v127, 0x3fb8aa3b, v127
	v_exp_f32_e32 v126, v126
	v_exp_f32_e32 v127, v127
	v_mfma_f32_16x16x32_bf16 v[122:125], v[224:227], v[166:169], v[122:125]
	s_nop 0
	v_add_f32_e64 v66, v66, -v114
	v_add_f32_e64 v67, v67, -v115
	v_pk_add_f32 v[64:65], v[64:65], v[116:117] neg_lo:[0,1] neg_hi:[0,1]
	v_pk_mul_f32 v[88:89], v[88:89], v[66:67]
	v_pk_mul_f32 v[114:115], v[126:127], v[64:65]
	v_mfma_f32_16x16x32_bf16 v[118:121], v[228:231], v[118:121], v[122:125]
	v_cvt_pk_bf16_f32 v66, v66, v67
	v_cvt_pk_bf16_f32 v88, v88, v89
	v_cvt_pk_bf16_f32 v67, v64, v65
	v_cvt_pk_bf16_f32 v89, v114, v115
	v_mul_f32_e32 v64, 0x3fb8aa3b, v87
	ds_write_b64 v100, v[88:89] offset:22016
	v_exp_f32_e32 v88, v64
	v_mul_f32_e32 v64, 0x3fb8aa3b, v110
	ds_write_b64 v101, v[66:67] offset:17408
	v_exp_f32_e32 v89, v64
	v_mul_f32_e32 v64, 0x3fb8aa3b, v153
	s_waitcnt lgkmcnt(0)
	s_barrier
	v_exp_f32_e32 v122, v64
	v_mul_f32_e32 v64, 0x3fb8aa3b, v155
	v_add_u32_e32 v110, v106, v94
	v_exp_f32_e32 v123, v64
	ds_read_b128 v[64:67], v110 offset:17408
	v_mfma_f32_16x16x32_bf16 v[114:117], v[232:235], v[170:173], v[118:121]
	v_ashrrev_i32_e32 v87, 31, v86
	s_nop 1
	ds_read_b128 v[118:121], v110 offset:17472
	s_nop 3
	v_pk_mul_f32 v[114:115], v[88:89], v[114:115]
	v_pk_mul_f32 v[116:117], v[122:123], v[116:117]
	v_lshlrev_b64 v[88:89], 11, v[86:87]
	v_lshl_add_u64 v[88:89], v[74:75], 0, v[88:89]
	s_waitcnt lgkmcnt(1)
	v_mfma_f32_16x16x32_bf16 v[64:67], v[146:149], v[64:67], v[114:117]
	s_waitcnt lgkmcnt(0)
	v_mfma_f32_16x16x32_bf16 v[64:67], v[158:161], v[118:121], v[64:67]
	s_nop 7
	v_mul_f32_e32 v114, v64, v64
	v_mul_f32_e32 v115, v65, v65
	v_mul_f32_e32 v116, v66, v66
	v_mul_f32_e32 v117, v67, v67
	v_mov_b32_dpp v114, v114 row_ror:8 row_mask:0xf bank_mask:0xf bound_ctrl:1
	v_mov_b32_dpp v115, v115 row_ror:8 row_mask:0xf bank_mask:0xf bound_ctrl:1
	v_mov_b32_dpp v116, v116 row_ror:8 row_mask:0xf bank_mask:0xf bound_ctrl:1
	v_mov_b32_dpp v117, v117 row_ror:8 row_mask:0xf bank_mask:0xf bound_ctrl:1
	v_fmac_f32_e32 v114, v64, v64
	v_fmac_f32_e32 v115, v65, v65
	v_fmac_f32_e32 v116, v66, v66
	v_fmac_f32_e32 v117, v67, v67
	v_add_f32_dpp v118, v114, v114 row_ror:4 row_mask:0xf bank_mask:0xf bound_ctrl:1
	v_add_f32_dpp v119, v115, v115 row_ror:4 row_mask:0xf bank_mask:0xf bound_ctrl:1
	v_add_f32_dpp v120, v116, v116 row_ror:4 row_mask:0xf bank_mask:0xf bound_ctrl:1
	v_add_f32_dpp v121, v117, v117 row_ror:4 row_mask:0xf bank_mask:0xf bound_ctrl:1
	v_add_f32_dpp v118, v118, v118 row_ror:2 row_mask:0xf bank_mask:0xf bound_ctrl:1
	v_add_f32_dpp v119, v119, v119 row_ror:2 row_mask:0xf bank_mask:0xf bound_ctrl:1
	v_add_f32_dpp v120, v120, v120 row_ror:2 row_mask:0xf bank_mask:0xf bound_ctrl:1
	v_add_f32_dpp v121, v121, v121 row_ror:2 row_mask:0xf bank_mask:0xf bound_ctrl:1
	v_mov_b32_dpp v114, v118 row_ror:1 row_mask:0xf bank_mask:0xf bound_ctrl:1
	v_mov_b32_dpp v115, v119 row_ror:1 row_mask:0xf bank_mask:0xf bound_ctrl:1
	v_mov_b32_dpp v116, v120 row_ror:1 row_mask:0xf bank_mask:0xf bound_ctrl:1
	v_mov_b32_dpp v117, v121 row_ror:1 row_mask:0xf bank_mask:0xf bound_ctrl:1
	v_add_f32_e32 v118, v118, v114
	v_add_f32_e32 v119, v119, v115
	v_add_f32_e32 v120, v120, v116
	v_add_f32_e32 v121, v121, v117
	v_cvt_pk_bf16_f32 v114, v64, v65
	v_cvt_pk_bf16_f32 v115, v66, v67
	v_mov_b32_dpp v119, v119 quad_perm:[0,0,0,0] row_mask:0xf bank_mask:0xf bound_ctrl:1
	v_mov_b32_dpp v120, v120 quad_perm:[0,0,0,0] row_mask:0xf bank_mask:0xf bound_ctrl:1
	v_mov_b32_dpp v121, v121 quad_perm:[0,0,0,0] row_mask:0xf bank_mask:0xf bound_ctrl:1
	v_mov_b32_dpp v116, v114 quad_perm:[2,3,0,1] row_mask:0xf bank_mask:0xf bound_ctrl:1
	v_mov_b32_dpp v117, v115 quad_perm:[2,3,0,1] row_mask:0xf bank_mask:0xf bound_ctrl:1
	v_cmp_eq_u32_e64 s[96:97], 1, v156
	v_cmp_eq_u32_e64 s[0:1], 2, v156
	v_and_b32_e32 v88, 2, v156
	v_cndmask_b32_e64 v118, v118, v119, s[96:97]
	v_cmp_eq_u32_e64 s[96:97], 3, v156
	v_cndmask_b32_e64 v118, v118, v120, s[0:1]
	v_cmp_ne_u32_e64 s[0:1], 0, v88
	v_cndmask_b32_e64 v118, v118, v121, s[96:97]
	v_add_u32_e32 v120, v86, v156
	v_mov_b32_e32 v121, 0
	v_cndmask_b32_e64 v114, v114, v117, s[0:1]
	v_cndmask_b32_e64 v115, v116, v115, s[0:1]
	v_lshlrev_b64 v[120:121], 8, v[120:121]
	v_add_u32_e32 v88, v86, v241
	v_mov_b32_dpp v116, v114 quad_perm:[1,0,3,2] row_mask:0xf bank_mask:0xf bound_ctrl:1
	v_mov_b32_dpp v117, v115 quad_perm:[1,0,3,2] row_mask:0xf bank_mask:0xf bound_ctrl:1
	v_lshl_add_u64 v[120:121], s[18:19], 0, v[120:121]
	v_mov_b32_e32 v89, 0
	v_perm_b32 v114, v116, v114, v240
	v_perm_b32 v115, v117, v115, v240
	v_lshlrev_b64 v[88:89], 11, v[88:89]
	v_cmp_gt_u32_e64 s[96:97], 4, v156
	v_lshl_add_u64 v[88:89], v[242:243], 0, v[88:89]
	global_store_dwordx2 v[88:89], v[114:115], off
	s_and_saveexec_b64 s[0:1], s[96:97]
	global_store_dword v[120:121], v118, off
	s_or_b64 exec, exec, s[0:1]
	v_mul_f32_e32 v64, 0x3fb8aa3b, v108
	v_exp_f32_e32 v108, v64
	ds_read_b128 v[64:67], v99 offset:22016
	ds_read_b128 v[86:89], v99 offset:24320
	ds_read_b128 v[114:117], v99 offset:22080
	ds_read_b128 v[118:121], v99 offset:24384
	v_pk_mul_f32 v[6:7], v[6:7], v[108:109] op_sel_hi:[1,0]
	v_pk_mul_f32 v[4:5], v[4:5], v[108:109] op_sel_hi:[1,0]
	v_pk_mul_f32 v[2:3], v[2:3], v[108:109] op_sel_hi:[1,0]
	v_pk_mul_f32 v[0:1], v[0:1], v[108:109] op_sel_hi:[1,0]
	s_waitcnt lgkmcnt(3)
	v_mfma_f32_16x16x32_bf16 v[4:7], v[60:63], v[64:67], v[4:7]
	s_waitcnt lgkmcnt(2)
	v_mfma_f32_16x16x32_bf16 v[0:3], v[60:63], v[86:89], v[0:3]
	s_waitcnt lgkmcnt(1)
	v_mfma_f32_16x16x32_bf16 v[4:7], v[56:59], v[114:117], v[4:7]
	s_waitcnt lgkmcnt(0)
	v_mfma_f32_16x16x32_bf16 v[0:3], v[56:59], v[118:121], v[0:3]
	s_cmpk_gt_u32 s8, 0x780
	s_cbranch_scc1 .LscanB_nostage
	s_cmpk_gt_u32 s8, 0x700
	s_cbranch_scc1 .LscanB_strict
	s_waitcnt vmcnt(13)
	s_branch .LscanB_wr

; __device__ __forceinline__ float bf2f(unsigned short b) { return __uint_as_float((unsigned)b << 16); }
; __device__ __forceinline__ void scan_load(ScanFrag& f, int n, int b, int h, int ti, int s, int li, int lq, int ucol, const bf16* Qg, const bf16* Kg, const bf16* Vg, const bf16* KT, const bf16* QK, const float* GC) {
;     const int gcid = b * 32 + n, m0 = b * 2048 + n * 64;
;     const bf16* wrow = Kg + (size_t)(m0 + 16 * ti + li) * D + h * 128 + 8 * lq; const bf16* qrow = Qg + (size_t)(m0 + 16 * ti + li) * D + h * 128 + 8 * lq;
; #pragma unroll
;     for (int ks = 0; ks < 4; ++ks) { f.wA[ks] = *(const bf16x8*)(wrow + 32 * ks); f.qA[ks] = *(const bf16x8*)(qrow + 32 * ks); }
;     const bf16* qkrow = QK + ((size_t)(gcid * 8 + h) * 64 + 16 * ti + li) * 64 + 8 * lq; const bf16* ktrow = KT + ((size_t)(gcid * 8 + h) * 128 + 16 * s + li) * 64 + 8 * lq;
; #pragma unroll
;     for (int k2 = 0; k2 < 2; ++k2) { f.qkA[k2] = *(const bf16x8*)(qkrow + 32 * k2); f.kA[k2] = *(const bf16x8*)(ktrow + 32 * k2); }
;     const int rowb = m0 + 16 * ti + 4 * lq;
; #pragma unroll
;     for (int r = 0; r < 4; ++r) { f.uval[r] = bf2f(Vg[(size_t)(rowb + r) * D + ucol]); f.gcr[r] = GC[(size_t)(rowb + r) * 8 + h]; }
;     f.gl = GC[(size_t)(m0 + 63) * 8 + h];
.LscanB_wr:
	ds_write_b128 v48, v[200:203]
	ds_write_b128 v48, v[204:207] offset:64
	ds_write_b128 v47, v[208:211]
	s_cmp_gt_u32 s95, 3
	s_cbranch_scc1 .Lscan_sw8u
	ds_write_b128 v49, v[212:215]
.Lscan_sw8u:
	s_cmp_lg_u32 s95, 0
	s_cbranch_scc1 .Lscan_sw8g
	ds_write_b32 v50, v216
.Lscan_sw8g:
	s_cmpk_gt_u32 s8, 0x700
	s_cbranch_scc1 .LscanB_nostage
	s_add_u32 s28, s28, 0x20000
	s_addc_u32 s29, s29, 0
	s_add_u32 s30, s30, 0x10000
	s_addc_u32 s31, s31, 0
	s_add_u32 s98, s98, 0x20000
	s_addc_u32 s99, s99, 0
	s_add_u32 s100, s100, 0x800
	s_addc_u32 s101, s101, 0
	global_load_dwordx4 v[200:203], v43, s[28:29]
	global_load_dwordx4 v[204:207], v44, s[28:29]
	global_load_dwordx4 v[208:211], v43, s[30:31]
	s_cmp_gt_u32 s95, 3
	s_cbranch_scc1 .Lscan_sl5u
	global_load_dwordx4 v[212:215], v45, s[98:99]

; __device__ __forceinline__ void scan_unit(LAS unsigned char* lds, int uidx, const bf16* Qg, const bf16* Kg, bf16* Vg, const bf16* KT, const bf16* QK, const float* GC, float* SSQ, float* sp_gdn) {
;     ...
;     for (int n = 0; n < 32; ++n) {
;         const int m0 = b * 2048 + n * 64, rowb = m0 + 16 * ti + 4 * lq;
;         __builtin_amdgcn_sched_barrier(0);
;         if (n + 1 < 32) scan_load(nxt, n + 1, b, h, ti, s, li, lq, ucol, Qg, Kg, Vg, KT, QK, GC);
;         __builtin_amdgcn_sched_barrier(0);
;     ...
;         __builtin_amdgcn_sched_barrier(0);
;         cur = nxt;
;     }
.Lscan_sl5g:
.LscanB_nostage:
	s_add_i32 s17, s17, 32
	s_add_i32 s8, s8, 64
	s_cmpk_eq_i32 s8, 0x800
	s_cbranch_scc0 .LBB0_833
	s_branch .Lscan_store
